# diff fast path: persistent bf16 ones operand in VGPRs for the row-sum MFMAs (no per-tile v_mov)
# baseline (speedup 1.0000x reference)
.LBB0_457:
	v_readlane_b32 s2, v254, 36
	s_add_i32 s7, s6, s2
	s_cmpk_gt_i32 s7, 0x7ff
	s_mov_b64 s[4:5], -1
	s_cbranch_scc1 .LBB0_456
	v_readlane_b32 s2, v253, 51
	v_readlane_b32 s4, v253, 49
	s_add_i32 s8, s6, s2
	s_ashr_i32 s9, s7, 5
	v_readlane_b32 s5, v253, 50
	s_and_b64 s[4:5], s[4:5], exec
	s_cselect_b32 s4, s85, s7
	s_cselect_b32 s5, s8, s9
	s_lshl_b32 s4, s4, 7
	s_and_b32 s16, s4, 0xf80
	s_lshl_b32 s4, s5, 7
	s_ashr_i32 s7, s5, 3
	s_and_b32 s8, s4, 0x380
	s_lshl_b32 s9, s7, 12
	s_lshl_b32 s10, s7, 8
	s_lshr_b32 s7, s8, 6
	s_add_i32 s10, s10, 0x8000
	s_mul_i32 s11, s7, 0x8800
	s_ashr_i32 s17, s9, 31
	v_mbcnt_lo_u32_b32 v0, -1, 0
	v_mbcnt_hi_u32_b32 v0, -1, v0
	s_add_u32 s4, s11, s9
	v_add_u32_e32 v187, s69, v0
	s_addc_u32 s5, 0, s17
	v_and_b32_e32 v0, 7, v187
	v_bfe_u32 v188, v187, 4, 2
	v_bitop3_b32 v0, v188, v0, s83 bitop3:0x36
	s_lshl_b64 s[4:5], s[4:5], 7
	v_and_or_b32 v0, v187, 56, v0
	s_add_u32 s12, s95, s4
	v_lshl_or_b32 v212, v0, 4, s46
	s_addc_u32 s13, s3, s5
	s_mov_b32 s19, m0
	s_mov_b32 m0, s23
	s_nop 0
	global_load_lds_dwordx4 v212, s[12:13]
	s_mov_b32 m0, s19
	s_add_i32 s12, s11, 0x8800
	s_add_u32 s28, s12, s9
	s_addc_u32 s29, 0, s17
	s_lshl_b64 s[28:29], s[28:29], 7
	v_bfe_u32 v5, v187, 5, 1
	v_lshlrev_b32_e32 v190, 4, v187
	s_add_u32 s28, s95, s28
	v_or_b32_e32 v2, s25, v5
	v_and_b32_e32 v3, 0x1c0, v190
	v_lshlrev_b32_e32 v189, 3, v187
	s_addc_u32 s29, s3, s29
	s_add_i32 s13, s23, 0x2000
	v_lshl_or_b32 v2, v2, 9, v3
	v_and_b32_e32 v6, 24, v189
	v_readlane_b32 s2, v253, 62
	s_add_u32 s4, s14, s4
	s_mov_b32 s17, m0
	s_mov_b32 m0, s13
	s_nop 0
	global_load_lds_dwordx4 v212, s[28:29]
	s_mov_b32 m0, s17
	s_addc_u32 s5, s15, s5
	v_or3_b32 v2, v2, s2, v6
	v_readlane_b32 s2, v253, 63
	s_add_i32 s13, s23, 0x4000
	v_and_b32_e32 v191, 31, v187
	v_add_lshl_u32 v222, v2, s2, 1
	s_mov_b32 s17, m0
	s_mov_b32 m0, s13
	s_nop 0
	global_load_lds_dwordx4 v222, s[4:5]
	s_mov_b32 m0, s17
	v_readlane_b32 s2, v254, 26
	s_add_i32 s13, s23, 0x6000
	v_lshlrev_b32_e32 v0, 4, v5
	v_add_lshl_u32 v223, v2, s2, 1
	s_mov_b32 s17, m0
	s_mov_b32 m0, s13
	s_nop 0
	global_load_lds_dwordx4 v223, s[4:5]
	s_mov_b32 m0, s17
	s_or_b32 s13, s9, 64
	s_ashr_i32 s17, s13, 31
	s_add_u32 s4, s11, s13
	s_addc_u32 s5, 0, s17
	s_lshl_b64 s[4:5], s[4:5], 7
	s_add_u32 s28, s95, s4
	s_addc_u32 s29, s3, s5
	s_add_i32 s19, s23, 0x8000
	s_mov_b32 s20, m0
	s_mov_b32 m0, s19
	s_nop 0
	global_load_lds_dwordx4 v212, s[28:29]
	s_mov_b32 m0, s20
	s_add_u32 s28, s12, s13
	s_addc_u32 s29, 0, s17
	s_lshl_b64 s[28:29], s[28:29], 7
	s_add_u32 s28, s95, s28
	s_addc_u32 s29, s3, s29
	s_add_i32 s13, s23, 0xa000
	s_mov_b32 s17, m0
	s_mov_b32 m0, s13
	s_nop 0
	global_load_lds_dwordx4 v212, s[28:29]
	s_mov_b32 m0, s17
	s_add_u32 s4, s14, s4
	s_addc_u32 s5, s15, s5
	s_add_i32 s13, s23, 0xc000
	s_mov_b32 s17, m0
	s_mov_b32 m0, s13
	s_nop 0
	global_load_lds_dwordx4 v222, s[4:5]
	s_mov_b32 m0, s17
	v_readlane_b32 s2, v254, 33
	s_add_i32 s13, s23, 0xe000
	s_mov_b32 s17, m0
	s_mov_b32 m0, s13
	s_nop 0
	global_load_lds_dwordx4 v223, s[4:5]
	s_mov_b32 m0, s17
	s_add_i32 s4, s7, s2
	v_readlane_b32 s2, v253, 53
	s_or_b32 s5, s16, s2
	s_or_b32 s7, s5, s9
	v_or_b32_e32 v2, s7, v191
	v_ashrrev_i32_e32 v3, 31, v2
	v_mad_u64_u32 v[2:3], s[4:5], s4, v217, v[2:3]
	v_lshlrev_b64 v[2:3], 7, v[2:3]
	v_lshl_add_u64 v[2:3], s[58:59], 0, v[2:3]
	v_lshl_add_u64 v[2:3], v[2:3], 0, v[0:1]
	global_load_dwordx4 v[144:147], v[2:3], off offset:96
	global_load_dwordx4 v[148:151], v[2:3], off offset:64
	global_load_dwordx4 v[152:155], v[2:3], off offset:32
	global_load_dwordx4 v[156:159], v[2:3], off
	v_lshrrev_b32_e32 v0, 1, v187
	v_lshrrev_b32_e32 v7, 2, v187
	v_lshlrev_b32_e32 v193, 2, v5
	v_lshlrev_b32_e32 v8, 1, v187
	v_bfe_u32 v9, v187, 1, 3
	v_bitop3_b32 v0, v5, v0, 7 bitop3:0x78
	v_and_or_b32 v7, v7, 3, v193
	v_lshlrev_b32_e32 v192, 3, v5
	v_and_b32_e32 v8, 32, v8
	v_bitop3_b32 v10, v5, v9, 2 bitop3:0x36
	v_bitop3_b32 v11, v5, v9, 4 bitop3:0x36
	v_bitop3_b32 v5, v5, v9, 6 bitop3:0x36
	v_lshlrev_b32_e32 v228, 4, v0
	v_lshlrev_b32_e32 v0, 6, v7
	v_mov_b32_e32 v14, v1
	v_mov_b32_e32 v15, v1
	v_mov_b32_e32 v2, v1
	v_mov_b32_e32 v3, v1
	v_mov_b32_e32 v4, v1
	v_lshlrev_b32_e32 v226, 4, v10
	v_lshlrev_b32_e32 v225, 4, v11
	v_lshlrev_b32_e32 v224, 4, v5
	v_or3_b32 v210, v0, v8, v6
	v_mov_b32_e32 v0, v1
	v_mov_b32_e32 v5, v1
	v_mov_b32_e32 v6, v1
	v_mov_b32_e32 v7, v1
	v_mov_b32_e32 v8, v1
	v_mov_b32_e32 v9, v1
	v_mov_b32_e32 v10, v1
	v_mov_b32_e32 v11, v1
	v_mov_b32_e32 v12, v1
	v_mov_b32_e32 v13, v1
	v_mov_b64_e32 v[78:79], v[14:15]
	v_mov_b64_e32 v[62:63], v[14:15]
	v_mov_b64_e32 v[46:47], v[14:15]
	v_mov_b64_e32 v[30:31], v[14:15]
	v_mov_b64_e32 v[94:95], v[14:15]
	s_mov_b32 s13, 2
	s_mov_b32 s19, 0
	v_and_b32_e32 v194, 63, v187
	v_lshl_add_u32 v227, v191, 7, s21
	v_add_u32_e32 v195, 0, v210
	s_mov_b64 s[4:5], -1
	v_mov_b32_e32 v209, 0
	v_mov_b32_e32 v140, 0
	v_mov_b32_e32 v141, 0
	v_mov_b32_e32 v142, 0
	v_mov_b32_e32 v143, 0
	v_mov_b32_e32 v136, 0
	v_mov_b32_e32 v137, 0
	v_mov_b32_e32 v138, 0
	v_mov_b32_e32 v139, 0
	v_mov_b32_e32 v132, 0
	v_mov_b32_e32 v133, 0
	v_mov_b32_e32 v134, 0
	v_mov_b32_e32 v135, 0
	v_mov_b32_e32 v128, 0
	v_mov_b32_e32 v129, 0
	v_mov_b32_e32 v130, 0
	v_mov_b32_e32 v131, 0
	v_mov_b64_e32 v[76:77], v[12:13]
	v_mov_b64_e32 v[74:75], v[10:11]
	v_mov_b64_e32 v[72:73], v[8:9]
	v_mov_b64_e32 v[70:71], v[6:7]
	v_mov_b64_e32 v[68:69], v[4:5]
	v_mov_b64_e32 v[66:67], v[2:3]
	v_mov_b64_e32 v[64:65], v[0:1]
	v_mov_b64_e32 v[60:61], v[12:13]
	v_mov_b64_e32 v[58:59], v[10:11]
	v_mov_b64_e32 v[56:57], v[8:9]
	v_mov_b64_e32 v[54:55], v[6:7]
	v_mov_b64_e32 v[52:53], v[4:5]
	v_mov_b64_e32 v[50:51], v[2:3]
	v_mov_b64_e32 v[48:49], v[0:1]
	v_mov_b64_e32 v[44:45], v[12:13]
	v_mov_b64_e32 v[42:43], v[10:11]
	v_mov_b64_e32 v[40:41], v[8:9]
	v_mov_b64_e32 v[38:39], v[6:7]
	v_mov_b64_e32 v[36:37], v[4:5]
	v_mov_b64_e32 v[34:35], v[2:3]
	v_mov_b64_e32 v[32:33], v[0:1]
	v_mov_b64_e32 v[28:29], v[12:13]
	v_mov_b64_e32 v[26:27], v[10:11]
	v_mov_b64_e32 v[24:25], v[8:9]
	v_mov_b64_e32 v[22:23], v[6:7]
	v_mov_b64_e32 v[20:21], v[4:5]
	v_mov_b64_e32 v[18:19], v[2:3]
	v_mov_b64_e32 v[16:17], v[0:1]
	v_mov_b64_e32 v[92:93], v[12:13]
	v_mov_b64_e32 v[90:91], v[10:11]
	v_mov_b64_e32 v[88:89], v[8:9]
	v_mov_b64_e32 v[86:87], v[6:7]
	v_mov_b64_e32 v[84:85], v[4:5]
	v_mov_b64_e32 v[82:83], v[2:3]
	v_mov_b64_e32 v[80:81], v[0:1]
	s_mov_b32 s28, 0
	s_waitcnt vmcnt(0)
	v_mov_b32_e32 v218, s60
	v_mov_b32_e32 v219, s60
	v_mov_b32_e32 v220, s60
	v_mov_b32_e32 v221, s60
	s_branch .Lf_460

.Lf_459:
	v_mov_b32_e32 v180, v128
	v_mov_b32_e32 v181, v129
	v_mov_b32_e32 v182, v130
	v_mov_b32_e32 v183, v131
	v_mfma_f32_32x32x16_bf16 v[64:79], v[176:179], v[140:143], v[64:79]
	ds_read_b64_tr_b16 v[128:129], v0 offset:24576
	ds_read_b64_tr_b16 v[130:131], v0 offset:25088
	v_exp_f32_e32 v14, v112
	s_mov_b32 s61, s60
	s_mov_b32 s62, s60
	s_mov_b32 s63, s60
	v_mfma_f32_32x32x16_bf16 v[64:79], v[172:175], v[136:139], v[64:79]
	ds_read_b64_tr_b16 v[172:173], v0 offset:25600
	ds_read_b64_tr_b16 v[174:175], v0 offset:26112
	v_exp_f32_e32 v15, v96
	v_mfma_f32_32x32x16_bf16 v[64:79], v[168:171], v[132:135], v[64:79]
	ds_read_b64_tr_b16 v[168:169], v0 offset:26624
	ds_read_b64_tr_b16 v[170:171], v0 offset:27136
	v_exp_f32_e32 v96, v113
	v_mfma_f32_32x32x16_bf16 v[64:79], v[164:167], v[180:183], v[64:79]
	ds_read_b64_tr_b16 v[164:165], v0 offset:27648
	ds_read_b64_tr_b16 v[166:167], v0 offset:28160
	v_exp_f32_e32 v97, v97
	v_mfma_f32_32x32x16_bf16 v[48:63], v[160:163], v[140:143], v[48:63]
	ds_read_b64_tr_b16 v[160:161], v0 offset:28672
	ds_read_b64_tr_b16 v[162:163], v0 offset:29184
	v_exp_f32_e32 v112, v114
	v_mfma_f32_32x32x16_bf16 v[48:63], v[10:13], v[136:139], v[48:63]
	ds_read_b64_tr_b16 v[10:11], v0 offset:29696
	ds_read_b64_tr_b16 v[12:13], v0 offset:30208
	v_exp_f32_e32 v98, v98
	v_mfma_f32_32x32x16_bf16 v[48:63], v[6:9], v[132:135], v[48:63]
	ds_read_b64_tr_b16 v[6:7], v0 offset:30720
	ds_read_b64_tr_b16 v[8:9], v0 offset:31232
	v_exp_f32_e32 v113, v115
	v_mfma_f32_32x32x16_bf16 v[48:63], v[2:5], v[180:183], v[48:63]
	ds_read_b64_tr_b16 v[2:3], v0 offset:31744
	ds_read_b64_tr_b16 v[4:5], v0 offset:32256
	v_exp_f32_e32 v0, v99
	s_waitcnt lgkmcnt(14)
	v_mfma_f32_32x32x16_bf16 v[32:47], v[128:131], v[140:143], v[32:47]
	v_exp_f32_e32 v99, v116
	v_exp_f32_e32 v100, v100
	v_exp_f32_e32 v114, v117
	s_waitcnt lgkmcnt(12)
	v_mfma_f32_32x32x16_bf16 v[32:47], v[172:175], v[136:139], v[32:47]
	v_exp_f32_e32 v101, v101
	v_exp_f32_e32 v115, v118
	v_exp_f32_e32 v102, v102
	s_waitcnt lgkmcnt(10)
	v_mfma_f32_32x32x16_bf16 v[32:47], v[168:171], v[132:135], v[32:47]
	v_exp_f32_e32 v116, v119
	v_exp_f32_e32 v103, v103
	v_exp_f32_e32 v117, v120
	s_waitcnt lgkmcnt(8)
	v_mfma_f32_32x32x16_bf16 v[32:47], v[164:167], v[180:183], v[32:47]
	v_exp_f32_e32 v104, v104
	v_exp_f32_e32 v118, v121
	v_exp_f32_e32 v105, v105
	s_waitcnt lgkmcnt(6)
	v_mfma_f32_32x32x16_bf16 v[16:31], v[160:163], v[140:143], v[16:31]
	v_exp_f32_e32 v119, v122
	v_exp_f32_e32 v106, v106
	v_exp_f32_e32 v120, v123
	s_waitcnt lgkmcnt(4)
	v_mfma_f32_32x32x16_bf16 v[16:31], v[10:13], v[136:139], v[16:31]
	v_exp_f32_e32 v10, v107
	v_exp_f32_e32 v11, v124
	v_exp_f32_e32 v12, v108
	s_waitcnt lgkmcnt(2)
	v_mfma_f32_32x32x16_bf16 v[16:31], v[6:9], v[132:135], v[16:31]
	v_exp_f32_e32 v6, v125
	v_exp_f32_e32 v7, v109
	v_exp_f32_e32 v8, v126
	s_waitcnt lgkmcnt(0)
	v_mfma_f32_32x32x16_bf16 v[16:31], v[2:5], v[180:183], v[16:31]
	v_exp_f32_e32 v107, v110
	s_nop 0
	v_mfma_f32_32x32x16_bf16 v[80:95], v[218:221], v[140:143], v[80:95]
	v_exp_f32_e32 v108, v127
	v_exp_f32_e32 v109, v111
	v_cvt_pk_bf16_f32 v140, v14, v96
	v_cvt_pk_bf16_f32 v143, v115, v116
	v_mfma_f32_32x32x16_bf16 v[80:95], v[218:221], v[136:139], v[80:95]
	v_cvt_pk_bf16_f32 v128, v104, v105
	v_cvt_pk_bf16_f32 v141, v112, v113
	v_cvt_pk_bf16_f32 v136, v117, v118
	v_mfma_f32_32x32x16_bf16 v[80:95], v[218:221], v[132:135], v[80:95]
	v_cvt_pk_bf16_f32 v137, v119, v120
	v_cvt_pk_bf16_f32 v129, v106, v10
	v_cvt_pk_bf16_f32 v132, v15, v97
	v_cvt_pk_bf16_f32 v130, v12, v7
	v_cvt_pk_bf16_f32 v138, v11, v6
	v_cvt_pk_bf16_f32 v133, v98, v0
	v_cvt_pk_bf16_f32 v142, v99, v114
	v_cvt_pk_bf16_f32 v134, v100, v101
	v_cvt_pk_bf16_f32 v135, v102, v103
	v_cvt_pk_bf16_f32 v139, v8, v108
	v_cvt_pk_bf16_f32 v131, v107, v109
	v_mfma_f32_32x32x16_bf16 v[80:95], v[218:221], v[180:183], v[80:95]
	s_add_i32 s28, s28, 1
	s_add_i32 s13, s13, 1
	s_add_i32 s19, s19, 0x8000
	s_cmpk_eq_i32 s13, 0x45
	s_cbranch_scc1 .LBB0_464

.Lf_462:
	s_and_b32 s17, s19, 0x18000
	v_add_u32_e32 v0, s17, v227
	v_add_u32_e32 v2, v0, v228
	ds_read_b128 v[96:99], v2
	ds_read_b128 v[100:103], v2 offset:4096
	v_add_u32_e32 v2, v0, v226
	ds_read_b128 v[180:183], v2
	ds_read_b128 v[230:233], v2 offset:4096
	v_add_u32_e32 v2, v0, v225
	v_add_u32_e32 v0, v0, v224
	s_min_u32 s16, s28, 1
	ds_read_b128 v[234:237], v2
	ds_read_b128 v[238:241], v2 offset:4096
	ds_read_b128 v[242:245], v0
	ds_read_b128 v[246:249], v0 offset:4096
	s_lshl_b32 s16, s16, 15
	s_sub_i32 s16, s19, s16
	s_and_b32 s16, s16, 0x18000
	v_add_u32_e32 v0, s16, v195
	s_setprio 1
	s_waitcnt lgkmcnt(6)
	v_mfma_f32_32x32x16_bf16 v[112:127], v[96:99], v[156:159], 0
	v_mfma_f32_32x32x16_bf16 v[96:111], v[100:103], v[156:159], 0
	s_waitcnt lgkmcnt(4)
	v_mfma_f32_32x32x16_bf16 v[112:127], v[180:183], v[152:155], v[112:127]
	v_mfma_f32_32x32x16_bf16 v[96:111], v[230:233], v[152:155], v[96:111]
	s_waitcnt lgkmcnt(2)
	v_mfma_f32_32x32x16_bf16 v[112:127], v[234:237], v[148:151], v[112:127]
	v_mfma_f32_32x32x16_bf16 v[96:111], v[238:241], v[148:151], v[96:111]
	s_waitcnt lgkmcnt(0)
	v_mfma_f32_32x32x16_bf16 v[112:127], v[242:245], v[144:147], v[112:127]
	v_mfma_f32_32x32x16_bf16 v[96:111], v[246:249], v[144:147], v[96:111]
	ds_read_b64_tr_b16 v[176:177], v0 offset:16384
	ds_read_b64_tr_b16 v[178:179], v0 offset:16896
	ds_read_b64_tr_b16 v[172:173], v0 offset:17408
	ds_read_b64_tr_b16 v[174:175], v0 offset:17920
	ds_read_b64_tr_b16 v[168:169], v0 offset:18432
	ds_read_b64_tr_b16 v[170:171], v0 offset:18944
	ds_read_b64_tr_b16 v[164:165], v0 offset:19456
	ds_read_b64_tr_b16 v[166:167], v0 offset:19968
	ds_read_b64_tr_b16 v[160:161], v0 offset:20480
	ds_read_b64_tr_b16 v[162:163], v0 offset:20992
	ds_read_b64_tr_b16 v[10:11], v0 offset:21504
	ds_read_b64_tr_b16 v[12:13], v0 offset:22016
	ds_read_b64_tr_b16 v[6:7], v0 offset:22528
	ds_read_b64_tr_b16 v[8:9], v0 offset:23040
	ds_read_b64_tr_b16 v[2:3], v0 offset:23552
	ds_read_b64_tr_b16 v[4:5], v0 offset:24064
	s_setprio 0
	v_max3_f32 v14, v112, v113, v114
	v_max3_f32 v15, v115, v116, v117
	v_max3_f32 v180, v118, v119, v120
	v_max3_f32 v181, v121, v122, v123
	v_max3_f32 v182, v124, v125, v126
	v_max3_f32 v183, v96, v97, v98
	v_max3_f32 v230, v99, v100, v101
	v_max3_f32 v231, v102, v103, v104
	s_nop 0
	v_max3_f32 v14, v14, v15, v180
	v_max3_f32 v232, v105, v106, v107
	v_max3_f32 v15, v181, v182, v127
	v_max3_f32 v233, v108, v109, v110
	s_xor_b64 s[30:31], s[4:5], -1
	v_max3_f32 v180, v183, v230, v231
	v_max3_f32 v181, v232, v233, v111
	s_nop 0
	v_max3_f32 v14, v14, v15, v180
	v_max_f32_e32 v14, v14, v181
	v_mov_b32_e32 v15, v14
	s_nop 1
	v_permlane32_swap_b32_e32 v15, v14
	v_max_f32_e32 v14, v14, v15
	v_cmp_lt_f32_e32 vcc, 0x42800000, v14
	s_waitcnt lgkmcnt(0)
	s_cbranch_vccz .Lf_459
	s_branch .Lf_to463
